# combo + dilated-attention items: touch-prefetch of the next item's K/V lines
# baseline (speedup 1.0000x reference)
; DI int tidx() { int t = threadIdx.x; asm volatile("" : "+v"(t)); return t; }
; DI void dil_item(const Params& p, int it, char* lds) {
;     ...
;   const int di = it >> 9, rem = it & 511, b = rem & 7, h = (rem >> 3) & 3, c = rem >> 5;
;   const int sh = 2 * di, dil = 1 << sh;
;   const int tpr = 16 >> sh;
;   const int r = c / tpr, mt = c % tpr, m0 = mt * 128;
;   const int tid = tidx(), lane = tid & 63, wid = tid >> 6, l31 = lane & 31, hi = lane >> 5;
;   const u16* proj = (const u16*)(ws_ + OFF_PROJ);
;   const int mq = m0 + 32 * wid + l31;
;   const size_t tok = (size_t)b * S_ + mq * dil + r;
;   bf16x8 qr[4];
; #pragma unroll
;   for (int s = 0; s < 4; ++s) qr[s] = *(const bf16x8*)(proj + tok * NP + C_BQ + h * 64 + 16 * s + 8 * hi);
;   const int tt0 = (m0 == 0) ? 2 : 0;
;   {
;     u32x4 pre[4][4];
; #pragma unroll
;     for (int tt = 0; tt < 4; ++tt)
;       if (tt >= tt0) kv_load(tid, pre[tt], [&](int row) { return b * S_ + (m0 - 128 + 64 * tt + row) * dil + r; }, proj, C_BK + h * 64, C_BV + h * 64);
.LBB0_268:
	s_mov_b64 s[0:1], 0
	s_add_u32 s10, s90, s0
	s_addc_u32 s11, s91, s1
	s_ashr_i32 s2, s8, 9
	s_lshl_b32 s13, s2, 1
	s_lshr_b32 s1, 16, s13
	s_bfe_u32 s0, s8, 0x40005
	s_add_i32 s1, s1, -1
	s_waitcnt vmcnt(10)
	v_mov_b32_e32 v84, v176
	s_sub_i32 s3, 4, s13
	s_and_b32 s12, s1, s0
	s_bfe_u32 s9, s8, 0x20003
	v_ashrrev_i32_e32 v85, 6, v84
	s_lshr_b32 s4, s0, s3
	s_lshl_b32 s3, s12, 7
	v_lshlrev_b32_e32 v83, 5, v85
	v_and_b32_e32 v82, 31, v84
	s_add_u32 s0, s10, 0x4a50000
	v_add_u32_e32 v0, s3, v83
	s_addc_u32 s1, s11, 0
	v_or_b32_e32 v0, v0, v82
	s_lshl_b32 s5, s8, 11
	s_and_b32 s5, s5, 0x3800
	v_lshlrev_b32_e32 v0, s13, v0
	v_ashrrev_i32_e32 v1, 31, v0
	s_or_b32 s80, s4, s5
	v_lshl_add_u64 v[112:113], v[0:1], 0, s[80:81]
	v_mov_b64_e32 v[0:1], s[0:1]
	v_mad_u64_u32 v[0:1], s[4:5], v112, s33, v[0:1]
	v_bfe_u32 v114, v84, 5, 1
	v_mad_i32_i24 v1, v113, s33, v1
	s_lshl_b32 s4, s9, 7
	s_mov_b32 s5, s81
	v_lshl_add_u64 v[0:1], v[0:1], 0, s[4:5]
	v_lshlrev_b32_e32 v178, 4, v114
	v_lshl_add_u64 v[0:1], v[0:1], 0, v[178:179]
	global_load_dwordx4 v[64:67], v[0:1], off offset:1792
	global_load_dwordx4 v[68:71], v[0:1], off offset:1824
	global_load_dwordx4 v[72:75], v[0:1], off offset:1856
	global_load_dwordx4 v[76:79], v[0:1], off offset:1888
	s_add_i32 s16, s8, 0x1c0
	s_cmpk_lt_i32 s16, 0x600
	s_cbranch_scc0 .Ldil_nopf
	s_ashr_i32 s17, s16, 9
	s_lshl_b32 s17, s17, 1
	s_lshr_b32 s18, 16, s17
	s_add_i32 s18, s18, -1
	s_bfe_u32 s19, s16, 0x40005
	s_and_b32 s20, s18, s19
	s_sub_i32 s21, 4, s17
	s_lshr_b32 s21, s19, s21
	s_lshl_b32 s20, s20, 7
	s_lshl_b32 s22, s16, 11
	s_and_b32 s22, s22, 0x3800
	s_or_b32 s21, s21, s22
	s_bfe_u32 s22, s16, 0x20003
	s_lshl_b32 s22, s22, 7
	s_add_i32 s20, s20, 0xffffff80
	v_add_u32_e32 v236, s20, v176
	v_max_i32_e32 v236, 0, v236
	v_lshlrev_b32_e32 v236, s17, v236
	v_add_u32_e32 v236, s21, v236
	v_mul_lo_u32 v236, v236, s33
	v_add_u32_e32 v236, s22, v236
	global_load_dword v237, v236, s[0:1] offset:2304
	global_load_dword v237, v236, s[0:1] offset:2816
.Ldil_nopf:
	s_lshl_b32 s14, s9, 6
	s_cmp_eq_u32 s12, 0
	v_lshlrev_b32_e32 v0, 4, v84
	s_cselect_b64 s[6:7], -1, 0
	s_cmp_lg_u32 s12, 0
	v_and_b32_e32 v80, 0x70, v0
	v_mov_b32_e32 v81, v179
	v_add_u32_e32 v0, 0x100, v84
	s_cselect_b64 s[4:5], -1, 0
	v_lshl_add_u64 v[56:57], s[0:1], 0, v[80:81]
	v_ashrrev_i32_e32 v81, 3, v84
	s_add_i32 s12, s3, 0xffffff80
	v_ashrrev_i32_e32 v86, 3, v0
	v_add_u32_e32 v48, s12, v81
	v_add_u32_e32 v58, s12, v86
	s_and_b64 vcc, exec, s[6:7]
	s_cbranch_vccnz .LBB0_270
	v_lshlrev_b32_e32 v0, s13, v48
	v_add_u32_e32 v0, s80, v0
	v_mad_i64_i32 v[0:1], s[0:1], v0, s33, v[56:57]
	s_lshl_b32 s0, s14, 1
	s_mov_b32 s1, s81
	v_lshl_add_u64 v[0:1], v[0:1], 0, s[0:1]
	global_load_dwordx4 v[12:15], v[0:1], off offset:2304
	global_load_dwordx4 v[4:7], v[0:1], off offset:2816
	v_lshlrev_b32_e32 v0, s13, v58
	v_add_u32_e32 v0, s80, v0
	v_mad_i64_i32 v[0:1], s[16:17], v0, s33, v[56:57]
	v_lshl_add_u64 v[0:1], v[0:1], 0, s[0:1]
	global_load_dwordx4 v[8:11], v[0:1], off offset:2304
	s_nop 0
	global_load_dwordx4 v[0:3], v[0:1], off offset:2816
